# XCD-local barriers at FFN1-FFN2, FFN2-norm, gate-branch, out-norm with norm rows remapped to the producing XCD; generalized placement check
# speedup vs baseline: 1.0082x; 1.0082x over previous
; #define LAS __attribute__((address_space(3)))
; __device__ __forceinline__ unsigned xb_add(unsigned* p, unsigned v) { return __hip_atomic_fetch_add(p, v, __ATOMIC_RELAXED, __HIP_MEMORY_SCOPE_AGENT); }
; __device__ __forceinline__ unsigned xb_xcc_id() { return (unsigned)__builtin_amdgcn_s_getreg((3 << 11) | 20) & 0xFu; }
; __device__ __forceinline__ XcdBarrier xcd_barrier_post(unsigned* bar, volatile LAS unsigned* st) {
;     XcdBarrier b; b.bar = bar; b.x = xb_xcc_id(); b.st = st;
;     if (threadIdx.x == 0) (void)xb_add(&bar[XB_XCNT(b.x)], 1u);
;     return b;
; __global__ void __launch_bounds__(NTHR) mega_fwd(Args a) {
;     ...
;     volatile LAS unsigned* xst = (volatile LAS unsigned*)(lds + LDS_BYTES - 16);
;     if (threadIdx.x == 0) { xst[0] = 0u; xst[1] = 0u; xst[2] = 0u; xst[3] = 0u; }
;     __syncthreads();
;     XcdBarrier xbar = xcd_barrier_post((unsigned*)(ws + WS_BAR), xst);
.LBB0_2:
	s_or_b64 exec, exec, s[2:3]
	s_load_dwordx16 s[4:19], s[0:1], 0x0
	s_load_dwordx16 s[76:91], s[0:1], 0x40
	s_waitcnt lgkmcnt(0)
	s_barrier
	v_writelane_b32 v249, s4, 12
	s_add_u32 s2, s72, 0x1d1d1000
	s_getreg_b32 s0, hwreg(HW_REG_XCC_ID, 0, 4)
	v_writelane_b32 v249, s5, 13
	v_writelane_b32 v249, s6, 14
	v_writelane_b32 v249, s7, 15
	v_writelane_b32 v249, s8, 16
	v_writelane_b32 v249, s9, 17
	v_writelane_b32 v249, s10, 18
	v_writelane_b32 v249, s11, 19
	v_writelane_b32 v249, s12, 20
	v_writelane_b32 v249, s13, 21
	v_writelane_b32 v249, s14, 22
	v_writelane_b32 v249, s15, 23
	v_writelane_b32 v249, s16, 24
	v_writelane_b32 v249, s17, 25
	v_writelane_b32 v249, s18, 26
	s_addc_u32 s3, s73, 0
	s_and_b32 s26, s0, 15
	v_writelane_b32 v249, s19, 27
	s_lshl_b32 s25, s26, 6
	s_mov_b64 s[0:1], exec
	v_readlane_b32 s4, v249, 10
	v_readlane_b32 s5, v249, 11
	s_and_b64 s[4:5], s[0:1], s[4:5]
	s_mov_b64 exec, s[4:5]
	s_cbranch_execz .LBB0_5
	s_mov_b64 s[4:5], exec
	v_mbcnt_lo_u32_b32 v1, s4, 0
	v_mbcnt_hi_u32_b32 v1, s5, v1
	v_cmp_eq_u32_e32 vcc, 0, v1
	s_and_b64 s[6:7], exec, vcc
	s_mov_b64 exec, s[6:7]
	s_cbranch_execz .LBB0_5
	s_lshl_b32 s6, s25, 2
	s_bcnt1_i32_b64 s4, s[4:5]
	v_mov_b32_e32 v1, s6
	v_mov_b32_e32 v2, s4
	global_atomic_add v1, v2, s[2:3] offset:1024
	s_and_b32 s4, s41, 7
	s_lshl_b32 s4, s4, 6
	s_add_u32 s4, s4, 16
	s_lshl_b32 s5, 1, s26
	s_cmpk_lg_u32 s74, 0x100
	s_cselect_b32 s6, 0x80000000, 0
	s_or_b32 s5, s5, s6
	v_mov_b32_e32 v5, s4
	v_mov_b32_e32 v6, s5
	global_atomic_or v5, v6, s[2:3]

; __device__ __forceinline__ int opaque_tid() { int t = (int)threadIdx.x; asm volatile("" : "+v"(t)); return t; }
; __device__ __forceinline__ void norm_phase(const void* xin, bool xin_bf, const bf16_t* y, const float* gpost, const float* mgate, float rw,
;                                            const float* gpre, const float* mshift, const float* mscale, void* xout, bool xout_bf, bf16_t* h) {
;     const int otid = opaque_tid();
;     const int lane = otid & 63, w = otid >> 6;
;     const int nw = gridDim.x * 8, rows_per = NTOK / nw;
;     const int gw = blockIdx.x * 8 + w;
;     const int r0 = gw * rows_per, b = r0 / SQ;
.LBB0_184:
	s_or_b64 exec, exec, s[0:1]
	s_add_u32 s92, s72, 0x3a00000
	s_addc_u32 s93, s73, 0
	s_lshl_b32 s0, s74, 3
	v_writelane_b32 v251, s0, 13
	s_abs_i32 s0, s0
	s_waitcnt lgkmcnt(0)
	v_cvt_f32_u32_e32 v0, s0
	s_sub_i32 s2, 0, s0
	s_bfe_i32 s1, s74, 0x1001c
	v_readlane_b32 s26, v250, 7
	v_rcp_iflag_f32_e32 v0, v0
	v_mov_b32_e32 v8, v199
	v_mbcnt_lo_u32_b32 v109, -1, 0
	v_readlane_b32 s27, v250, 8
	v_mul_f32_e32 v0, 0x4f7ffffe, v0
	v_cvt_u32_f32_e32 v0, v0
	s_barrier
	v_readlane_b32 s4, v249, 10
	v_readlane_b32 s5, v249, 11
	s_mov_b64 s[6:7], exec
	s_and_b64 s[4:5], s[6:7], s[4:5]
	s_mov_b64 exec, s[4:5]
	s_cbranch_execz .Ldec_skip
	v_readlane_b32 s4, v251, 9
	v_readlane_b32 s5, v251, 10
	s_sub_u32 s4, s4, 0x3400
	s_subb_u32 s5, s5, 0
	v_mov_b32_e32 v5, 0
	global_load_dword v6, v5, s[4:5] offset:16 sc1
	global_load_dword v7, v5, s[4:5] offset:80 sc1
	global_load_dword v9, v5, s[4:5] offset:144 sc1
	global_load_dword v10, v5, s[4:5] offset:208 sc1
	global_load_dword v11, v5, s[4:5] offset:272 sc1
	global_load_dword v12, v5, s[4:5] offset:336 sc1
	global_load_dword v13, v5, s[4:5] offset:400 sc1
	global_load_dword v18, v5, s[4:5] offset:464 sc1
	s_and_b32 s8, s41, 7
	s_lshl_b32 s8, s8, 6
	s_add_u32 s8, s8, 1
	s_mov_b32 s9, 0
	s_waitcnt vmcnt(0)
	v_readfirstlane_b32 s10, v6
	s_sub_u32 s11, s10, 1
	s_and_b32 s11, s11, s10
	s_or_b32 s9, s9, s11
	s_cmp_eq_u32 s10, 0
	s_cselect_b32 s11, 1, 0
	s_or_b32 s9, s9, s11
	v_readfirstlane_b32 s10, v7
	s_sub_u32 s11, s10, 1
	s_and_b32 s11, s11, s10
	s_or_b32 s9, s9, s11
	s_cmp_eq_u32 s10, 0
	s_cselect_b32 s11, 1, 0
	s_or_b32 s9, s9, s11
	v_readfirstlane_b32 s10, v9
	s_sub_u32 s11, s10, 1
	s_and_b32 s11, s11, s10
	s_or_b32 s9, s9, s11
	s_cmp_eq_u32 s10, 0
	s_cselect_b32 s11, 1, 0
	s_or_b32 s9, s9, s11
	v_readfirstlane_b32 s10, v10
	s_sub_u32 s11, s10, 1
	s_and_b32 s11, s11, s10
	s_or_b32 s9, s9, s11
	s_cmp_eq_u32 s10, 0
	s_cselect_b32 s11, 1, 0
	s_or_b32 s9, s9, s11
	v_readfirstlane_b32 s10, v11
	s_sub_u32 s11, s10, 1
	s_and_b32 s11, s11, s10
	s_or_b32 s9, s9, s11
	s_cmp_eq_u32 s10, 0
	s_cselect_b32 s11, 1, 0
	s_or_b32 s9, s9, s11
	v_readfirstlane_b32 s10, v12
	s_sub_u32 s11, s10, 1
	s_and_b32 s11, s11, s10
	s_or_b32 s9, s9, s11
	s_cmp_eq_u32 s10, 0
	s_cselect_b32 s11, 1, 0
	s_or_b32 s9, s9, s11
	v_readfirstlane_b32 s10, v13
	s_sub_u32 s11, s10, 1
	s_and_b32 s11, s11, s10
	s_or_b32 s9, s9, s11
	s_cmp_eq_u32 s10, 0
	s_cselect_b32 s11, 1, 0
	s_or_b32 s9, s9, s11
	v_readfirstlane_b32 s10, v18
	s_sub_u32 s11, s10, 1
	s_and_b32 s11, s11, s10
	s_or_b32 s9, s9, s11
	s_cmp_eq_u32 s10, 0
	s_cselect_b32 s11, 1, 0
	s_or_b32 s9, s9, s11
	s_cmp_eq_u32 s9, 0
	s_cselect_b32 s8, s8, 0
	v_mov_b32_e32 v7, s8
	v_mov_b32_e32 v5, 0x23ffc
	ds_write_b32 v5, v7
	s_waitcnt lgkmcnt(0)
.Ldec_skip:
	s_mov_b64 exec, s[6:7]
	v_readfirstlane_b32 s3, v0
	s_mul_i32 s2, s2, s3
	s_mul_hi_u32 s2, s3, s2
	s_add_i32 s3, s3, s2
	s_lshr_b32 s2, s3, 17
	s_mul_i32 s3, s2, s0
	s_sub_i32 s3, 0x8000, s3
	s_add_i32 s4, s2, 1
	s_sub_i32 s5, s3, s0
	s_cmp_ge_u32 s3, s0
	s_cselect_b32 s2, s4, s2
	s_cselect_b32 s3, s5, s3
	s_add_i32 s4, s2, 1
	s_cmp_ge_u32 s3, s0
	s_cselect_b32 s0, s4, s2
	s_xor_b32 s0, s0, s1
	s_sub_i32 s0, s0, s1
	s_lshl_b32 s1, s41, 3
	s_cmpk_lg_u32 s74, 0x100
	s_cbranch_scc1 .Lnoremap
	s_and_b32 s1, s41, 7
	s_lshl_b32 s1, s1, 5
	s_lshr_b32 s2, s41, 3
	s_or_b32 s1, s1, s2
	s_lshl_b32 s1, s1, 3
; __device__ __forceinline__ void norm_load(NormRows& R, const void* xin, bool xin_bf, const bf16_t* y, int r, int lane) {
; #pragma unroll
;     for (int q = 0; q < 2; ++q)
; #pragma unroll
;         for (int s = 0; s < 4; ++s) {
;             const size_t e = (size_t)(r + q) * DM + s * 256 + lane * 4;
;             if (xin_bf) { const u32x2 t = __builtin_nontemporal_load((const u32x2*)((const bf16_t*)xin + e));
;                 R.xv[q][s] = (f32x4){__uint_as_float(t.x << 16), __uint_as_float(t.x & 0xffff0000u), __uint_as_float(t.y << 16), __uint_as_float(t.y & 0xffff0000u)}; }
;             else R.xv[q][s] = __builtin_nontemporal_load((const f32x4*)((const float*)xin + e));
; __device__ __forceinline__ void norm_phase(const void* xin, bool xin_bf, const bf16_t* y, const float* gpost, const float* mgate, float rw,
;                                            const float* gpre, const float* mshift, const float* mscale, void* xout, bool xout_bf, bf16_t* h) {
;     ...
;     f32x4 gp[4], pa[4];
; #pragma unroll
;     for (int s = 0; s < 4; ++s) {
;         const int c = s * 256 + lane * 4;
;         if (y) { const f32x4 g1 = *(const f32x4*)(mgate + b * 9216 + c), g2 = *(const f32x4*)(gpost + c); gp[s] = g1 * g2 * rw; } else gp[s] = (f32x4){0.f, 0.f, 0.f, 0.f};
;         if (h) { const f32x4 g1 = *(const f32x4*)(gpre + c), g2 = *(const f32x4*)(mscale + b * 9216 + c); pa[s] = g1 * (g2 + 1.f); }
;         else { pa[s] = (f32x4){0.f, 0.f, 0.f, 0.f}; }
;     }
;     NormRows A, B;
;     norm_load(A, xin, xin_bf, y, r0, lane);
.Lnoremap:
	v_writelane_b32 v249, s1, 56
	s_cmp_gt_i32 s0, 0
	v_writelane_b32 v249, s0, 57
	s_cselect_b64 s[0:1], -1, 0
	v_writelane_b32 v251, s0, 14
	s_and_b64 vcc, exec, s[0:1]
	s_nop 0
	v_writelane_b32 v251, s1, 15
	s_cbranch_vccz .LBB0_190
	v_ashrrev_i32_e32 v0, 6, v8
	v_readlane_b32 s0, v249, 56
	v_readlane_b32 s3, v249, 57
	v_lshlrev_b32_e32 v1, 2, v8
	v_add_u32_e32 v0, s0, v0
	v_mul_lo_u32 v4, v0, s3
	v_ashrrev_i32_e32 v5, 31, v4
	v_lshrrev_b32_e32 v0, 20, v5
	v_add_u32_e32 v0, v4, v0
	v_ashrrev_i32_e32 v0, 12, v0
	v_mul_i32_i24_e32 v0, 0x2400, v0
	v_and_b32_e32 v38, 0xfc, v1
	v_ashrrev_i32_e32 v1, 31, v0
	v_lshlrev_b64 v[6:7], 2, v[0:1]
	v_lshl_add_u64 v[0:1], s[72:73], 0, v[6:7]
	v_lshlrev_b32_e32 v68, 2, v38
	v_mov_b32_e32 v69, 0
	v_lshl_add_u64 v[10:11], v[0:1], 0, v[68:69]
	s_mov_b32 s2, 0x1d101000
	v_add_co_u32_e32 v0, vcc, s2, v10
	s_mov_b64 s[0:1], 0x1d101000
	s_nop 0
	v_addc_co_u32_e32 v1, vcc, 0, v11, vcc
	global_load_dwordx4 v[0:3], v[0:1], off
	v_readlane_b32 s4, v249, 12
	v_lshl_add_u64 v[18:19], v[10:11], 0, s[0:1]
	v_readlane_b32 s12, v249, 20
	v_readlane_b32 s13, v249, 21
	global_load_dwordx4 v[10:13], v[18:19], off offset:1024
	global_load_dwordx4 v[14:17], v[18:19], off offset:2048
	s_nop 0
	global_load_dwordx4 v[18:21], v[18:19], off offset:3072
	s_nop 0
	global_load_dwordx4 v[22:25], v68, s[12:13]
	global_load_dwordx4 v[26:29], v68, s[12:13] offset:1024
	global_load_dwordx4 v[30:33], v68, s[12:13] offset:2048
	global_load_dwordx4 v[34:37], v68, s[12:13] offset:3072
	v_mbcnt_hi_u32_b32 v40, -1, v109
	v_and_b32_e32 v39, 64, v40
	v_xor_b32_e32 v41, 32, v40
	v_add_u32_e32 v48, 64, v39
	v_xor_b32_e32 v43, 16, v40
	v_cmp_lt_i32_e32 vcc, v41, v48
	v_xor_b32_e32 v44, 8, v40
	v_readlane_b32 s5, v249, 13
	v_cndmask_b32_e32 v41, v40, v41, vcc
	v_cmp_lt_i32_e32 vcc, v43, v48
	v_xor_b32_e32 v45, 4, v40
	v_xor_b32_e32 v46, 2, v40
	v_cndmask_b32_e32 v43, v40, v43, vcc
	v_cmp_lt_i32_e32 vcc, v44, v48
	v_readlane_b32 s6, v249, 14
	v_readlane_b32 s7, v249, 15
	v_cndmask_b32_e32 v44, v40, v44, vcc
	v_cmp_lt_i32_e32 vcc, v45, v48
	v_and_b32_e32 v42, 63, v8
	v_mov_b32_e32 v9, v69
	v_xor_b32_e32 v47, 1, v40
	v_lshlrev_b32_e32 v8, 1, v38
	v_cndmask_b32_e32 v45, v40, v45, vcc
	v_cmp_lt_i32_e32 vcc, v46, v48
	v_readlane_b32 s6, v249, 58
	v_lshl_add_u64 v[70:71], s[92:93], 0, v[8:9]
	v_cndmask_b32_e32 v46, v40, v46, vcc
	v_cmp_lt_i32_e32 vcc, v47, v48
	v_lshlrev_b64 v[8:9], 12, v[4:5]
	v_readlane_b32 s7, v249, 59
	v_cndmask_b32_e32 v40, v40, v47, vcc
	v_lshl_add_u64 v[8:9], s[4:5], 0, v[8:9]
	s_movk_i32 s2, 0x1000
	v_lshl_add_u64 v[38:39], s[6:7], 0, v[68:69]
	v_lshlrev_b32_e32 v111, 2, v41
	v_lshlrev_b32_e32 v116, 2, v40
	v_lshl_add_u64 v[40:41], v[8:9], 0, v[68:69]
	s_mov_b64 s[0:1], 0x1000
	v_lshl_add_u64 v[76:77], v[38:39], 0, v[6:7]
	v_add_u32_e32 v110, s3, v4
	v_add_u32_e32 v74, 5, v4
	v_lshl_add_u64 v[8:9], v[40:41], 0, s[0:1]
	v_readlane_b32 s10, v249, 18
	v_lshl_add_u64 v[72:73], s[4:5], 0, v[68:69]
	v_lshlrev_b32_e32 v112, 2, v43
	v_lshlrev_b32_e32 v113, 2, v44
	v_lshlrev_b32_e32 v114, 2, v45
	v_lshlrev_b32_e32 v115, 2, v46
	v_lshlrev_b32_e32 v68, 4, v42
	v_lshlrev_b32_e32 v96, 3, v42
	v_mov_b32_e32 v97, v69
	s_mov_b64 s[0:1], 0
	s_mov_b32 s3, 0x800000
	s_mov_b32 s10, 0x3a00000
	s_mov_b64 s[6:7], 0x2000
	v_mov_b32_e32 v108, 0x358637bd
	v_readlane_b32 s8, v249, 16
	v_readlane_b32 s9, v249, 17
	v_readlane_b32 s11, v249, 19
	v_readlane_b32 s14, v249, 22
	v_readlane_b32 s15, v249, 23
	v_readlane_b32 s16, v249, 24
	v_readlane_b32 s17, v249, 25
	v_readlane_b32 s18, v249, 26
	v_readlane_b32 s19, v249, 27
	s_waitcnt vmcnt(7)
	v_pk_add_f32 v[0:1], v[0:1], 1.0 op_sel_hi:[1,0]
	v_pk_add_f32 v[2:3], v[2:3], 1.0 op_sel_hi:[1,0]
	s_waitcnt vmcnt(3)
	v_pk_mul_f32 v[80:81], v[22:23], v[0:1]
	v_add_u32_e32 v0, 4, v4
	v_ashrrev_i32_e32 v1, 31, v0
	v_lshlrev_b64 v[0:1], 12, v[0:1]
	v_lshl_add_u64 v[94:95], s[4:5], 0, v[0:1]
	v_lshlrev_b64 v[0:1], 11, v[4:5]
	v_lshl_add_u64 v[98:99], s[72:73], 0, v[0:1]
	v_add_u32_e32 v0, 2, v4
	v_ashrrev_i32_e32 v1, 31, v0
	v_pk_mul_f32 v[78:79], v[24:25], v[2:3]
	v_lshlrev_b64 v[2:3], 11, v[0:1]
	v_lshl_add_u64 v[100:101], s[72:73], 0, v[2:3]
	v_add_u32_e32 v2, 3, v4
	v_pk_add_f32 v[6:7], v[12:13], 1.0 op_sel_hi:[1,0]
	v_pk_add_f32 v[12:13], v[16:17], 1.0 op_sel_hi:[1,0]
	v_pk_add_f32 v[16:17], v[20:21], 1.0 op_sel_hi:[1,0]
	v_add_co_u32_e32 v20, vcc, s2, v40
	v_ashrrev_i32_e32 v3, 31, v2
	v_pk_add_f32 v[10:11], v[10:11], 1.0 op_sel_hi:[1,0]
	v_pk_add_f32 v[14:15], v[14:15], 1.0 op_sel_hi:[1,0]
	v_pk_add_f32 v[18:19], v[18:19], 1.0 op_sel_hi:[1,0]
	v_addc_co_u32_e32 v21, vcc, 0, v41, vcc
	v_lshlrev_b64 v[4:5], 12, v[2:3]
	v_lshlrev_b64 v[2:3], 11, v[2:3]
	v_lshlrev_b64 v[0:1], 12, v[0:1]
	s_waitcnt vmcnt(2)
	v_pk_mul_f32 v[82:83], v[28:29], v[6:7]
	v_pk_mul_f32 v[84:85], v[26:27], v[10:11]
	s_waitcnt vmcnt(1)
	v_pk_mul_f32 v[86:87], v[32:33], v[12:13]
	v_pk_mul_f32 v[88:89], v[30:31], v[14:15]
	s_waitcnt vmcnt(0)
	v_pk_mul_f32 v[90:91], v[36:37], v[16:17]
	v_pk_mul_f32 v[92:93], v[34:35], v[18:19]
	v_lshl_add_u64 v[102:103], s[4:5], 0, v[4:5]
	v_lshl_add_u64 v[104:105], s[72:73], 0, v[2:3]
	v_lshl_add_u64 v[106:107], s[4:5], 0, v[0:1]
	global_load_dwordx4 v[0:3], v[8:9], off offset:2048 nt
	global_load_dwordx4 v[4:7], v[8:9], off offset:1024 nt
	global_load_dwordx4 v[12:15], v[8:9], off offset:3072 nt
	s_nop 0
	global_load_dwordx4 v[8:11], v[20:21], off nt
	global_load_dwordx4 v[16:19], v[40:41], off offset:3072 nt
	s_nop 0
	global_load_dwordx4 v[20:23], v[40:41], off offset:2048 nt
	global_load_dwordx4 v[24:27], v[40:41], off offset:1024 nt
	global_load_dwordx4 v[28:31], v[40:41], off nt
	s_mov_b32 s2, 0x3a800000
	s_mov_b64 s[4:5], 0x4000
	s_branch .LBB0_187

; __device__ __forceinline__ unsigned xb_add(unsigned* p, unsigned v) { return __hip_atomic_fetch_add(p, v, __ATOMIC_RELAXED, __HIP_MEMORY_SCOPE_AGENT); }
; __device__ __forceinline__ void xcd_barrier(const XcdBarrier& b) {
;     asm volatile("s_waitcnt vmcnt(0)" ::: "memory");
;     __syncthreads();
;     if (threadIdx.x == 0) {
;         unsigned* bar = b.bar;
;         __builtin_amdgcn_s_waitcnt(0);
;         unsigned nloc = b.st[0], nx = b.st[1];
;         if (nloc == 0u) { xcd_barrier_complete(bar, b.x, nloc, nx); b.st[0] = nloc; b.st[1] = nx; }
;         const unsigned old = xb_add(&bar[XB_XSUB(b.x)], 1u);
.LBB0_338:
	s_waitcnt vmcnt(0)
	s_barrier
	s_waitcnt vmcnt(0)
	s_barrier
	s_mov_b64 s[0:1], exec
	v_readlane_b32 s2, v249, 10
	v_readlane_b32 s3, v249, 11
	s_and_b64 s[2:3], s[0:1], s[2:3]
	s_mov_b64 exec, s[2:3]
	s_cbranch_execz .LBB0_390
	v_mov_b32_e32 v2, 0x23ffc
	ds_read_b32 v3, v2
	v_readlane_b32 s4, v251, 9
	v_readlane_b32 s5, v251, 10
	s_waitcnt lgkmcnt(0)
	v_readfirstlane_b32 s6, v3
	s_cmp_eq_u32 s6, 0
	s_cbranch_scc1 .Llbfull_390
	s_cmp_eq_u32 s97, 1
	s_cbranch_scc1 .Llbfull_390
	buffer_inv sc1
	s_add_u32 s6, s6, 0xffffcbff
	s_add_u32 s4, s4, s6
	s_addc_u32 s5, s5, -1
	v_mov_b32_e32 v2, 0x23ff8
	ds_read_b32 v3, v2
	v_mov_b32_e32 v5, 0
	v_mov_b32_e32 v6, 1
	global_atomic_add v5, v6, s[4:5]
	s_waitcnt lgkmcnt(0)
	v_add_u32_e32 v3, 1, v3
	ds_write_b32 v2, v3
	v_lshlrev_b32_e32 v3, 5, v3
